# no full store drain (vmcnt(0)) at the attention queue-loop top and MLA prologue start: the previous unit's Y stores overlap the next unit's first loads
# baseline (speedup 1.0000x reference)
.LBB0_764:
	s_and_saveexec_b64 s[0:1], s[44:45]
	v_mov_b32_e32 v2, s33
	ds_write_b32 v2, v230
	s_or_b64 exec, exec, s[0:1]
	s_waitcnt lgkmcnt(0)
	s_barrier
	ds_read_b32 v2, v231
	s_movk_i32 s0, 0x883
	s_waitcnt lgkmcnt(0)
	v_cmp_lt_i32_e64 s[4:5], s0, v2
	v_readfirstlane_b32 s74, v2
	s_and_b64 vcc, exec, s[4:5]
	s_cbranch_vccnz .LBB0_763
	s_and_saveexec_b64 s[0:1], s[44:45]
	s_cbranch_execz .LBB0_771
	s_mov_b64 s[8:9], exec
	v_mbcnt_lo_u32_b32 v2, s8, 0
	v_mbcnt_hi_u32_b32 v2, s9, v2
	v_cmp_eq_u32_e32 vcc, 0, v2
	s_and_saveexec_b64 s[6:7], vcc
	s_cbranch_execz .LBB0_770
	s_bcnt1_i32_b64 s8, s[8:9]
	v_mov_b32_e32 v4, s8
	global_atomic_add v4, v3, v4, s[66:67] sc0

.LBB0_949:
	s_lshl_b64 s[0:1], s[26:27], 11
	s_add_u32 s0, s22, s0
	s_addc_u32 s1, s23, s1
	s_lshl_b32 s6, s75, 7
	v_and_b32_e32 v233, 63, v19
	s_add_u32 s0, s0, s6
	s_addc_u32 s1, s1, 0
	v_lshlrev_b32_e32 v2, 11, v233
	s_lshl_b32 s6, s24, 3

	v_lshl_add_u64 v[4:5], s[0:1], 0, v[2:3]
	s_ashr_i32 s7, s6, 31
	v_lshl_add_u64 v[16:17], s[6:7], 1, v[4:5]
	v_add_u32_e32 v2, s26, v233
	v_readlane_b32 s6, v252, 37
	v_lshlrev_b64 v[4:5], 6, v[2:3]
	v_readlane_b32 s7, v252, 38
	s_lshl_b32 s40, s24, 10
	s_add_i32 s40, s40, 0
	v_lshl_add_u64 v[4:5], s[6:7], 0, v[4:5]
	s_bfe_u32 s6, s8, 0x20006
	s_lshl_b32 s7, s6, 10
	s_or_b32 s43, s7, 0x2000
	s_lshl_b32 s26, s6, 4
	s_add_i32 s43, s43, 0
	s_mov_b32 s7, m0
	s_mov_b32 m0, s40
	s_nop 0
	global_load_lds_dwordx4 v[16:17], off
	s_mov_b32 m0, s7
	s_cmp_lt_i32 s24, 4
	s_waitcnt lgkmcnt(7)
	v_lshl_add_u64 v[222:223], v[4:5], 0, s[26:27]
	s_cselect_b64 s[92:93], -1, 0
	s_cmp_gt_i32 s24, 3
	s_cbranch_scc1 .LBB0_951
	s_mov_b32 s7, m0
	s_mov_b32 m0, s43
	s_nop 0
	global_load_lds_dwordx4 v[222:223], off
	s_mov_b32 m0, s7
